# gate outputs (rho, sigmoid gB) stored non-temporal so the last-level cache keeps attention inputs; plus LN row-stat shuffles via v_permlane swaps instead of ds_bpermute
# speedup vs baseline: 1.0010x; 1.0010x over previous
; __device__ __forceinline__ unsigned cvt_pk_bf16(float lo, float hi) { f32x2_t v = {lo, hi}; bf16x2_t r = __builtin_convertvector(v, bf16x2_t); return __builtin_bit_cast(unsigned, r); }
; __device__ __forceinline__ float f8c(float v) { return fminf(fmaxf(v, -448.f), 448.f); }
;     __device__ __forceinline__ void operator()(const f32x4 (&acc)[2][2][4][2], const Unit& u, int wr, int wc, int fr, int fq) const {
;     ...
;             const int c0 = 128 * (pn - 26) + lc;
;             f32x4 bA[2], bB[2];
; #pragma unroll
;             for (int n = 0; n < 2; ++n) { bA[n] = *(const f32x4*)(bias + 6656 + c0 + 4 * n); bB[n] = *(const f32x4*)(bias + 7680 + c0 + 4 * n); }
; #pragma unroll
;             for (int ai = 0; ai < 2; ++ai)
; #pragma unroll
;                 for (int m = 0; m < 4; ++m) { const size_t off = (size_t)(row0 + ai * 128 + m * 16) * D + c0; f32x4 rh[2], sb[2];
; #pragma unroll
;                     for (int n = 0; n < 2; ++n) { const f32x4 a = acc[ai][0][m][n] * as + bA[n], b = acc[ai][1][m][n] * as + bB[n];
; #pragma unroll
;                         for (int j = 0; j < 4; ++j) { const float ea = 1.f + __builtin_amdgcn_exp2f(-a[j] * LOG2E), eb = 1.f + __builtin_amdgcn_exp2f(-b[j] * LOG2E); sb[n][j] = __builtin_amdgcn_rcpf(eb); rh[n][j] = eb * __builtin_amdgcn_rcpf(ea); } }
;                     int r0 = 0, r1 = 0; r0 = __builtin_amdgcn_cvt_pk_fp8_f32(f8c(rh[0][0]), f8c(rh[0][1]), r0, false); r0 = __builtin_amdgcn_cvt_pk_fp8_f32(f8c(rh[0][2]), f8c(rh[0][3]), r0, true);
;                     r1 = __builtin_amdgcn_cvt_pk_fp8_f32(f8c(rh[1][0]), f8c(rh[1][1]), r1, false); r1 = __builtin_amdgcn_cvt_pk_fp8_f32(f8c(rh[1][2]), f8c(rh[1][3]), r1, true);
;                     u32x2 w0; w0.x = (unsigned)r0; w0.y = (unsigned)r1; u32x4 w1;
;                     w1.x = cvt_pk_bf16(sb[0][0], sb[0][1]); w1.y = cvt_pk_bf16(sb[0][2], sb[0][3]); w1.z = cvt_pk_bf16(sb[1][0], sb[1][1]); w1.w = cvt_pk_bf16(sb[1][2], sb[1][3]);
;                     *(u32x2*)((unsigned char*)GA + off) = w0; *(u32x4*)(GB + off) = w1; }
.LBB0_186:
	s_cmp_lg_u32 s34, 9
	v_ashrrev_i32_e32 v155, 31, v154
	s_cbranch_scc0 .LBB0_188
	s_lshl_b32 s30, s34, 7
	s_addk_i32 s30, 0xf300
	v_add_u32_e32 v160, s30, v158
	v_ashrrev_i32_e32 v161, 31, v160
	v_lshlrev_b64 v[128:129], 2, v[160:161]
	v_lshl_add_u64 v[130:131], s[20:21], 0, v[128:129]
	v_lshl_add_u64 v[136:137], s[22:23], 0, v[128:129]
	global_load_dwordx4 v[132:135], v[130:131], off offset:16
	global_load_dwordx4 v[140:143], v[130:131], off
	s_nop 0
	global_load_dwordx4 v[128:131], v[136:137], off offset:16
	s_nop 0
	global_load_dwordx4 v[136:139], v[136:137], off
	v_lshlrev_b64 v[162:163], 10, v[154:155]
	v_lshl_add_u64 v[160:161], v[162:163], 0, v[160:161]
	v_readlane_b32 s36, v250, 22
	v_readlane_b32 s37, v250, 23
	v_readlane_b32 s38, v250, 24
	v_readlane_b32 s39, v250, 25
	s_mov_b64 s[30:31], 0x8000
	s_waitcnt vmcnt(0)
	v_fmamk_f32 v146, v120, 0x3d000000, v140
	v_mul_f32_e32 v146, 0xbfb8aa3b, v146
	v_exp_f32_e32 v146, v146
	v_fmamk_f32 v168, v119, 0x3d000000, v139
	v_mul_f32_e32 v168, 0xbfb8aa3b, v168
	v_exp_f32_e32 v168, v168
	v_add_f32_e32 v157, 1.0, v146
	v_fmamk_f32 v146, v116, 0x3d000000, v136
	v_mul_f32_e32 v146, 0xbfb8aa3b, v146
	v_exp_f32_e32 v146, v146
	v_rcp_f32_e32 v157, v157
	v_add_f32_e32 v168, 1.0, v168
	v_rcp_f32_e32 v180, v168
	v_add_f32_e32 v159, 1.0, v146
	v_rcp_f32_e32 v146, v159
	v_mul_f32_e32 v157, v159, v157
	v_fmamk_f32 v159, v121, 0x3d000000, v141
	v_mul_f32_e32 v159, 0xbfb8aa3b, v159
	v_exp_f32_e32 v159, v159
	v_fmamk_f32 v169, v112, 0x3d000000, v128
	v_mul_f32_e32 v169, 0xbfb8aa3b, v169
	v_exp_f32_e32 v169, v169
	v_add_f32_e32 v164, 1.0, v159
	v_fmamk_f32 v159, v117, 0x3d000000, v137
	v_mul_f32_e32 v159, 0xbfb8aa3b, v159
	v_exp_f32_e32 v159, v159
	v_rcp_f32_e32 v164, v164
	v_add_f32_e32 v169, 1.0, v169
	v_rcp_f32_e32 v181, v169
	v_add_f32_e32 v165, 1.0, v159
	v_rcp_f32_e32 v159, v165
	v_mul_f32_e32 v164, v165, v164
	v_fmamk_f32 v165, v122, 0x3d000000, v142
	v_mul_f32_e32 v165, 0xbfb8aa3b, v165
	v_exp_f32_e32 v165, v165
	v_fmamk_f32 v182, v113, 0x3d000000, v129
	v_mul_f32_e32 v182, 0xbfb8aa3b, v182
	v_exp_f32_e32 v182, v182
	v_add_f32_e32 v166, 1.0, v165
	v_fmamk_f32 v165, v118, 0x3d000000, v138
	v_mul_f32_e32 v165, 0xbfb8aa3b, v165
	v_exp_f32_e32 v165, v165
	v_rcp_f32_e32 v166, v166
	v_add_f32_e32 v182, 1.0, v182
	v_rcp_f32_e32 v183, v182
	v_add_f32_e32 v167, 1.0, v165
	v_rcp_f32_e32 v165, v167
	v_mul_f32_e32 v166, v167, v166
	v_fmamk_f32 v167, v123, 0x3d000000, v143
	v_mul_f32_e32 v167, 0xbfb8aa3b, v167
	v_exp_f32_e32 v167, v167
	v_fmamk_f32 v184, v114, 0x3d000000, v130
	v_mul_f32_e32 v184, 0xbfb8aa3b, v184
	v_exp_f32_e32 v184, v184
	v_add_f32_e32 v167, 1.0, v167
	v_rcp_f32_e32 v167, v167
	v_fmamk_f32 v186, v115, 0x3d000000, v131
	v_add_f32_e32 v184, 1.0, v184
	v_rcp_f32_e32 v185, v184
	v_mul_f32_e32 v167, v168, v167
	v_fmamk_f32 v168, v124, 0x3d000000, v132
	v_mul_f32_e32 v168, 0xbfb8aa3b, v168
	v_exp_f32_e32 v168, v168
	v_mul_f32_e32 v186, 0xbfb8aa3b, v186
	v_exp_f32_e32 v186, v186
	v_med3_f32 v157, v157, s66, v179
	v_add_f32_e32 v168, 1.0, v168
	v_rcp_f32_e32 v168, v168
	v_add_f32_e32 v186, 1.0, v186
	v_rcp_f32_e32 v187, v186
	v_med3_f32 v162, v164, s66, v179
	v_mul_f32_e32 v169, v169, v168
	v_fmamk_f32 v168, v125, 0x3d000000, v133
	v_mul_f32_e32 v168, 0xbfb8aa3b, v168
	v_exp_f32_e32 v168, v168
	v_cvt_pk_bf16_f32 v163, v165, v180
	v_cvt_pk_bf16_f32 v164, v181, v183
	v_cvt_pk_bf16_f32 v165, v185, v187
	v_add_f32_e32 v168, 1.0, v168
	v_rcp_f32_e32 v168, v168
	s_nop 0
	v_mul_f32_e32 v182, v182, v168
	v_fmamk_f32 v168, v126, 0x3d000000, v134
	v_mul_f32_e32 v168, 0xbfb8aa3b, v168
	v_exp_f32_e32 v168, v168
	s_nop 0
	v_add_f32_e32 v168, 1.0, v168
	v_rcp_f32_e32 v168, v168
	s_nop 0
	v_mul_f32_e32 v184, v184, v168
	v_fmamk_f32 v168, v127, 0x3d000000, v135
	v_mul_f32_e32 v168, 0xbfb8aa3b, v168
	v_exp_f32_e32 v168, v168
	s_nop 0
	v_add_f32_e32 v168, 1.0, v168
	v_rcp_f32_e32 v168, v168
	s_nop 0
	v_mul_f32_e32 v186, v186, v168
	v_mov_b32_e32 v168, v147
	v_cvt_pk_fp8_f32 v168, v157, v162
	v_med3_f32 v157, v166, s66, v179
	v_med3_f32 v162, v167, s66, v179
	v_lshl_add_u64 v[166:167], s[36:37], 0, v[160:161]
	v_cvt_pk_fp8_f32 v168, v157, v162 op_sel:[0,0,1]
	v_med3_f32 v157, v169, s66, v179
	v_med3_f32 v162, v182, s66, v179
	v_mov_b32_e32 v169, v147
	v_cvt_pk_fp8_f32 v169, v157, v162
	v_med3_f32 v157, v184, s66, v179
	v_med3_f32 v162, v186, s66, v179
	v_cvt_pk_fp8_f32 v169, v157, v162 op_sel:[0,0,1]
	v_cvt_pk_bf16_f32 v162, v146, v159
	v_fmamk_f32 v146, v108, 0x3d000000, v140
	v_mul_f32_e32 v146, 0xbfb8aa3b, v146
	v_exp_f32_e32 v146, v146
	v_fmamk_f32 v157, v100, 0x3d000000, v136
	v_mul_f32_e32 v157, 0xbfb8aa3b, v157
	v_exp_f32_e32 v157, v157
	v_add_f32_e32 v146, 1.0, v146
	v_rcp_f32_e32 v146, v146
	global_store_dwordx2 v[166:167], v[168:169], off nt
	v_add_f32_e32 v157, 1.0, v157
	v_rcp_f32_e32 v159, v157
	v_mul_f32_e32 v146, v157, v146
	v_fmamk_f32 v157, v109, 0x3d000000, v141
	v_mul_f32_e32 v157, 0xbfb8aa3b, v157
	v_exp_f32_e32 v157, v157
	v_lshl_add_u64 v[166:167], v[160:161], 1, s[38:39]
	global_store_dwordx4 v[166:167], v[162:165], off nt
	v_fmamk_f32 v166, v103, 0x3d000000, v139
	v_add_f32_e32 v157, 1.0, v157
	v_fmamk_f32 v162, v101, 0x3d000000, v137
	v_mul_f32_e32 v162, 0xbfb8aa3b, v162
	v_exp_f32_e32 v162, v162
	v_rcp_f32_e32 v157, v157
	v_fmamk_f32 v164, v102, 0x3d000000, v138
	v_mul_f32_e32 v164, 0xbfb8aa3b, v164
	v_add_f32_e32 v162, 1.0, v162
	v_rcp_f32_e32 v163, v162
	v_mul_f32_e32 v157, v162, v157
	v_fmamk_f32 v162, v110, 0x3d000000, v142
	v_mul_f32_e32 v162, 0xbfb8aa3b, v162
	v_exp_f32_e32 v162, v162
	v_exp_f32_e32 v164, v164
	v_mul_f32_e32 v166, 0xbfb8aa3b, v166
	v_exp_f32_e32 v166, v166
; __device__ __forceinline__ unsigned cvt_pk_bf16(float lo, float hi) { f32x2_t v = {lo, hi}; bf16x2_t r = __builtin_convertvector(v, bf16x2_t); return __builtin_bit_cast(unsigned, r); }
; __device__ __forceinline__ float f8c(float v) { return fminf(fmaxf(v, -448.f), 448.f); }
;     __device__ __forceinline__ void operator()(const f32x4 (&acc)[2][2][4][2], const Unit& u, int wr, int wc, int fr, int fq) const {
;     ...
;             const int c0 = 128 * (pn - 26) + lc;
;             f32x4 bA[2], bB[2];
; #pragma unroll
;             for (int n = 0; n < 2; ++n) { bA[n] = *(const f32x4*)(bias + 6656 + c0 + 4 * n); bB[n] = *(const f32x4*)(bias + 7680 + c0 + 4 * n); }
; #pragma unroll
;             for (int ai = 0; ai < 2; ++ai)
; #pragma unroll
;                 for (int m = 0; m < 4; ++m) { const size_t off = (size_t)(row0 + ai * 128 + m * 16) * D + c0; f32x4 rh[2], sb[2];
; #pragma unroll
;                     for (int n = 0; n < 2; ++n) { const f32x4 a = acc[ai][0][m][n] * as + bA[n], b = acc[ai][1][m][n] * as + bB[n];
; #pragma unroll
;                         for (int j = 0; j < 4; ++j) { const float ea = 1.f + __builtin_amdgcn_exp2f(-a[j] * LOG2E), eb = 1.f + __builtin_amdgcn_exp2f(-b[j] * LOG2E); sb[n][j] = __builtin_amdgcn_rcpf(eb); rh[n][j] = eb * __builtin_amdgcn_rcpf(ea); } }
;                     int r0 = 0, r1 = 0; r0 = __builtin_amdgcn_cvt_pk_fp8_f32(f8c(rh[0][0]), f8c(rh[0][1]), r0, false); r0 = __builtin_amdgcn_cvt_pk_fp8_f32(f8c(rh[0][2]), f8c(rh[0][3]), r0, true);
;                     r1 = __builtin_amdgcn_cvt_pk_fp8_f32(f8c(rh[1][0]), f8c(rh[1][1]), r1, false); r1 = __builtin_amdgcn_cvt_pk_fp8_f32(f8c(rh[1][2]), f8c(rh[1][3]), r1, true);
;                     u32x2 w0; w0.x = (unsigned)r0; w0.y = (unsigned)r1; u32x4 w1;
;                     w1.x = cvt_pk_bf16(sb[0][0], sb[0][1]); w1.y = cvt_pk_bf16(sb[0][2], sb[0][3]); w1.z = cvt_pk_bf16(sb[1][0], sb[1][1]); w1.w = cvt_pk_bf16(sb[1][2], sb[1][3]);
;                     *(u32x2*)((unsigned char*)GA + off) = w0; *(u32x4*)(GB + off) = w1; }
	v_add_f32_e32 v162, 1.0, v162
	v_rcp_f32_e32 v162, v162
	v_add_f32_e32 v164, 1.0, v164
	v_rcp_f32_e32 v165, v164
	v_add_f32_e32 v166, 1.0, v166
	v_mul_f32_e32 v162, v164, v162
	v_fmamk_f32 v164, v111, 0x3d000000, v143
	v_mul_f32_e32 v164, 0xbfb8aa3b, v164
	v_exp_f32_e32 v164, v164
	v_rcp_f32_e32 v180, v166
	v_fmamk_f32 v167, v96, 0x3d000000, v128
	v_mul_f32_e32 v167, 0xbfb8aa3b, v167
	v_add_f32_e32 v164, 1.0, v164
	v_rcp_f32_e32 v164, v164
	v_exp_f32_e32 v167, v167
	v_med3_f32 v146, v146, s66, v179
	v_med3_f32 v157, v157, s66, v179
	v_mul_f32_e32 v164, v166, v164
	v_fmamk_f32 v166, v104, 0x3d000000, v132
	v_mul_f32_e32 v166, 0xbfb8aa3b, v166
	v_exp_f32_e32 v166, v166
	v_add_f32_e32 v167, 1.0, v167
	v_rcp_f32_e32 v181, v167
	v_mov_b32_e32 v168, v147
	v_add_f32_e32 v166, 1.0, v166
	v_rcp_f32_e32 v166, v166
	v_cvt_pk_fp8_f32 v168, v146, v157
	v_med3_f32 v146, v162, s66, v179
	v_med3_f32 v157, v164, s66, v179
	v_mul_f32_e32 v169, v167, v166
	v_fmamk_f32 v166, v105, 0x3d000000, v133
	v_mul_f32_e32 v166, 0xbfb8aa3b, v166
	v_exp_f32_e32 v166, v166
	v_fmamk_f32 v167, v97, 0x3d000000, v129
	v_mul_f32_e32 v167, 0xbfb8aa3b, v167
	v_exp_f32_e32 v167, v167
	v_add_f32_e32 v166, 1.0, v166
	v_rcp_f32_e32 v166, v166
	v_cvt_pk_fp8_f32 v168, v146, v157 op_sel:[0,0,1]
	v_add_f32_e32 v167, 1.0, v167
	v_rcp_f32_e32 v182, v167
	v_mul_f32_e32 v183, v167, v166
	v_fmamk_f32 v166, v106, 0x3d000000, v134
	v_mul_f32_e32 v166, 0xbfb8aa3b, v166
	v_exp_f32_e32 v166, v166
	v_fmamk_f32 v167, v98, 0x3d000000, v130
	v_mul_f32_e32 v167, 0xbfb8aa3b, v167
	v_exp_f32_e32 v167, v167
	v_add_f32_e32 v166, 1.0, v166
	v_rcp_f32_e32 v166, v166
	v_med3_f32 v146, v169, s66, v179
	v_add_f32_e32 v167, 1.0, v167
	v_rcp_f32_e32 v184, v167
	v_mul_f32_e32 v185, v167, v166
	v_fmamk_f32 v166, v107, 0x3d000000, v135
	v_mul_f32_e32 v166, 0xbfb8aa3b, v166
	v_exp_f32_e32 v166, v166
	v_fmamk_f32 v167, v99, 0x3d000000, v131
	v_mul_f32_e32 v167, 0xbfb8aa3b, v167
	v_exp_f32_e32 v167, v167
	v_add_f32_e32 v166, 1.0, v166
	v_rcp_f32_e32 v166, v166
	v_med3_f32 v157, v183, s66, v179
	v_mov_b32_e32 v169, v147
	v_cvt_pk_fp8_f32 v169, v146, v157
	v_add_f32_e32 v167, 1.0, v167
	v_mul_f32_e32 v187, v167, v166
	v_med3_f32 v146, v185, s66, v179
	v_med3_f32 v157, v187, s66, v179
	v_cvt_pk_fp8_f32 v169, v146, v157 op_sel:[0,0,1]
	v_fmamk_f32 v146, v92, 0x3d000000, v140
	v_mul_f32_e32 v146, 0xbfb8aa3b, v146
	v_exp_f32_e32 v146, v146
	v_fmamk_f32 v157, v84, 0x3d000000, v136
	v_mul_f32_e32 v157, 0xbfb8aa3b, v157
	v_exp_f32_e32 v157, v157
	v_add_f32_e32 v146, 1.0, v146
	v_rcp_f32_e32 v146, v146
	v_rcp_f32_e32 v186, v167
	v_add_f32_e32 v157, 1.0, v157
	v_cvt_pk_bf16_f32 v162, v159, v163
	v_rcp_f32_e32 v159, v157
	v_mul_f32_e32 v146, v157, v146
	v_fmamk_f32 v157, v93, 0x3d000000, v141
	v_mul_f32_e32 v157, 0xbfb8aa3b, v157
	v_lshl_add_u64 v[166:167], v[160:161], 0, s[26:27]
	v_exp_f32_e32 v157, v157
	v_cvt_pk_bf16_f32 v163, v165, v180
	v_cvt_pk_bf16_f32 v164, v181, v182
	v_cvt_pk_bf16_f32 v165, v184, v186
	v_lshl_add_u64 v[180:181], s[36:37], 0, v[166:167]
	v_lshl_add_u64 v[166:167], v[166:167], 1, s[38:39]
	global_store_dwordx2 v[180:181], v[168:169], off nt
	global_store_dwordx4 v[166:167], v[162:165], off nt
	v_add_f32_e32 v157, 1.0, v157
	v_rcp_f32_e32 v157, v157
	v_fmamk_f32 v162, v85, 0x3d000000, v137
	v_mul_f32_e32 v162, 0xbfb8aa3b, v162
	v_exp_f32_e32 v162, v162
	v_fmamk_f32 v164, v86, 0x3d000000, v138
	v_mul_f32_e32 v164, 0xbfb8aa3b, v164
	v_exp_f32_e32 v164, v164
	v_add_f32_e32 v162, 1.0, v162
	v_rcp_f32_e32 v163, v162
	v_mul_f32_e32 v157, v162, v157
	v_fmamk_f32 v162, v94, 0x3d000000, v142
	v_mul_f32_e32 v162, 0xbfb8aa3b, v162
	v_exp_f32_e32 v162, v162
	v_add_f32_e32 v164, 1.0, v164
	v_rcp_f32_e32 v165, v164
	v_fmamk_f32 v166, v87, 0x3d000000, v139
	v_add_f32_e32 v162, 1.0, v162
	v_rcp_f32_e32 v162, v162
	v_mul_f32_e32 v166, 0xbfb8aa3b, v166
	v_exp_f32_e32 v166, v166
	v_fmamk_f32 v167, v80, 0x3d000000, v128
	v_mul_f32_e32 v162, v164, v162
	v_fmamk_f32 v164, v95, 0x3d000000, v143
	v_mul_f32_e32 v164, 0xbfb8aa3b, v164
	v_exp_f32_e32 v164, v164
	v_add_f32_e32 v166, 1.0, v166
	v_rcp_f32_e32 v180, v166
	v_mul_f32_e32 v167, 0xbfb8aa3b, v167
	v_add_f32_e32 v164, 1.0, v164
	v_rcp_f32_e32 v164, v164
	v_exp_f32_e32 v167, v167
	v_med3_f32 v146, v146, s66, v179
	v_med3_f32 v157, v157, s66, v179
	v_mul_f32_e32 v164, v166, v164
	v_fmamk_f32 v166, v88, 0x3d000000, v132
	v_mul_f32_e32 v166, 0xbfb8aa3b, v166
	v_exp_f32_e32 v166, v166
	v_add_f32_e32 v167, 1.0, v167
	v_rcp_f32_e32 v181, v167
	v_mov_b32_e32 v168, v147
	v_add_f32_e32 v166, 1.0, v166
	v_rcp_f32_e32 v166, v166
	v_cvt_pk_fp8_f32 v168, v146, v157
	v_med3_f32 v146, v162, s66, v179
	v_med3_f32 v157, v164, s66, v179
	v_mul_f32_e32 v169, v167, v166
	v_fmamk_f32 v166, v89, 0x3d000000, v133
	v_mul_f32_e32 v166, 0xbfb8aa3b, v166
	v_exp_f32_e32 v166, v166
	v_fmamk_f32 v167, v81, 0x3d000000, v129
	v_mul_f32_e32 v167, 0xbfb8aa3b, v167
	v_exp_f32_e32 v167, v167
	v_add_f32_e32 v166, 1.0, v166
	v_rcp_f32_e32 v166, v166
	v_cvt_pk_fp8_f32 v168, v146, v157 op_sel:[0,0,1]
	v_add_f32_e32 v167, 1.0, v167
	v_rcp_f32_e32 v182, v167
	v_mul_f32_e32 v183, v167, v166
	v_fmamk_f32 v166, v90, 0x3d000000, v134
	v_mul_f32_e32 v166, 0xbfb8aa3b, v166
	v_exp_f32_e32 v166, v166
	v_fmamk_f32 v167, v82, 0x3d000000, v130
	v_mul_f32_e32 v167, 0xbfb8aa3b, v167
	v_exp_f32_e32 v167, v167
	v_add_f32_e32 v166, 1.0, v166
	v_rcp_f32_e32 v166, v166
	v_med3_f32 v146, v169, s66, v179
	v_add_f32_e32 v167, 1.0, v167
	v_rcp_f32_e32 v184, v167
	v_mul_f32_e32 v185, v167, v166
	v_fmamk_f32 v166, v91, 0x3d000000, v135
	v_mul_f32_e32 v166, 0xbfb8aa3b, v166
	v_exp_f32_e32 v166, v166
	v_fmamk_f32 v167, v83, 0x3d000000, v131
; __device__ __forceinline__ unsigned cvt_pk_bf16(float lo, float hi) { f32x2_t v = {lo, hi}; bf16x2_t r = __builtin_convertvector(v, bf16x2_t); return __builtin_bit_cast(unsigned, r); }
; __device__ __forceinline__ float f8c(float v) { return fminf(fmaxf(v, -448.f), 448.f); }
;     __device__ __forceinline__ void operator()(const f32x4 (&acc)[2][2][4][2], const Unit& u, int wr, int wc, int fr, int fq) const {
;     ...
;             const int c0 = 128 * (pn - 26) + lc;
;             f32x4 bA[2], bB[2];
; #pragma unroll
;             for (int n = 0; n < 2; ++n) { bA[n] = *(const f32x4*)(bias + 6656 + c0 + 4 * n); bB[n] = *(const f32x4*)(bias + 7680 + c0 + 4 * n); }
; #pragma unroll
;             for (int ai = 0; ai < 2; ++ai)
; #pragma unroll
;                 for (int m = 0; m < 4; ++m) { const size_t off = (size_t)(row0 + ai * 128 + m * 16) * D + c0; f32x4 rh[2], sb[2];
; #pragma unroll
;                     for (int n = 0; n < 2; ++n) { const f32x4 a = acc[ai][0][m][n] * as + bA[n], b = acc[ai][1][m][n] * as + bB[n];
; #pragma unroll
;                         for (int j = 0; j < 4; ++j) { const float ea = 1.f + __builtin_amdgcn_exp2f(-a[j] * LOG2E), eb = 1.f + __builtin_amdgcn_exp2f(-b[j] * LOG2E); sb[n][j] = __builtin_amdgcn_rcpf(eb); rh[n][j] = eb * __builtin_amdgcn_rcpf(ea); } }
;                     int r0 = 0, r1 = 0; r0 = __builtin_amdgcn_cvt_pk_fp8_f32(f8c(rh[0][0]), f8c(rh[0][1]), r0, false); r0 = __builtin_amdgcn_cvt_pk_fp8_f32(f8c(rh[0][2]), f8c(rh[0][3]), r0, true);
;                     r1 = __builtin_amdgcn_cvt_pk_fp8_f32(f8c(rh[1][0]), f8c(rh[1][1]), r1, false); r1 = __builtin_amdgcn_cvt_pk_fp8_f32(f8c(rh[1][2]), f8c(rh[1][3]), r1, true);
;                     u32x2 w0; w0.x = (unsigned)r0; w0.y = (unsigned)r1; u32x4 w1;
;                     w1.x = cvt_pk_bf16(sb[0][0], sb[0][1]); w1.y = cvt_pk_bf16(sb[0][2], sb[0][3]); w1.z = cvt_pk_bf16(sb[1][0], sb[1][1]); w1.w = cvt_pk_bf16(sb[1][2], sb[1][3]);
;                     *(u32x2*)((unsigned char*)GA + off) = w0; *(u32x4*)(GB + off) = w1; }
	v_mul_f32_e32 v167, 0xbfb8aa3b, v167
	v_exp_f32_e32 v167, v167
	v_add_f32_e32 v166, 1.0, v166
	v_rcp_f32_e32 v166, v166
	v_med3_f32 v157, v183, s66, v179
	v_mov_b32_e32 v169, v147
	v_cvt_pk_fp8_f32 v169, v146, v157
	v_add_f32_e32 v167, 1.0, v167
	v_mul_f32_e32 v187, v167, v166
	v_med3_f32 v146, v185, s66, v179
	v_med3_f32 v157, v187, s66, v179
	v_cvt_pk_fp8_f32 v169, v146, v157 op_sel:[0,0,1]
	v_fmamk_f32 v146, v76, 0x3d000000, v140
	v_mul_f32_e32 v146, 0xbfb8aa3b, v146
	v_exp_f32_e32 v146, v146
	v_fmamk_f32 v157, v68, 0x3d000000, v136
	v_mul_f32_e32 v157, 0xbfb8aa3b, v157
	v_exp_f32_e32 v157, v157
	v_add_f32_e32 v146, 1.0, v146
	v_rcp_f32_e32 v146, v146
	v_rcp_f32_e32 v186, v167
	v_add_f32_e32 v157, 1.0, v157
	v_cvt_pk_bf16_f32 v162, v159, v163
	v_rcp_f32_e32 v159, v157
	v_mul_f32_e32 v146, v157, v146
	v_fmamk_f32 v157, v77, 0x3d000000, v141
	v_mul_f32_e32 v157, 0xbfb8aa3b, v157
	v_lshl_add_u64 v[166:167], v[160:161], 0, s[30:31]
	v_exp_f32_e32 v157, v157
	v_cvt_pk_bf16_f32 v163, v165, v180
	v_cvt_pk_bf16_f32 v164, v181, v182
	v_cvt_pk_bf16_f32 v165, v184, v186
	v_lshl_add_u64 v[180:181], s[36:37], 0, v[166:167]
	v_lshl_add_u64 v[166:167], v[166:167], 1, s[38:39]
	global_store_dwordx2 v[180:181], v[168:169], off nt
	global_store_dwordx4 v[166:167], v[162:165], off nt
	v_add_f32_e32 v157, 1.0, v157
	v_rcp_f32_e32 v157, v157
	v_fmamk_f32 v162, v69, 0x3d000000, v137
	v_mul_f32_e32 v162, 0xbfb8aa3b, v162
	v_exp_f32_e32 v162, v162
	v_fmamk_f32 v164, v70, 0x3d000000, v138
	v_mul_f32_e32 v164, 0xbfb8aa3b, v164
	v_exp_f32_e32 v164, v164
	v_add_f32_e32 v162, 1.0, v162
	v_rcp_f32_e32 v163, v162
	v_mul_f32_e32 v157, v162, v157
	v_fmamk_f32 v162, v78, 0x3d000000, v142
	v_mul_f32_e32 v162, 0xbfb8aa3b, v162
	v_exp_f32_e32 v162, v162
	v_add_f32_e32 v164, 1.0, v164
	v_rcp_f32_e32 v165, v164
	v_fmamk_f32 v166, v71, 0x3d000000, v139
	v_add_f32_e32 v162, 1.0, v162
	v_rcp_f32_e32 v162, v162
	v_mul_f32_e32 v166, 0xbfb8aa3b, v166
	v_exp_f32_e32 v166, v166
	v_fmamk_f32 v167, v64, 0x3d000000, v128
	v_mul_f32_e32 v162, v164, v162
	v_fmamk_f32 v164, v79, 0x3d000000, v143
	v_mul_f32_e32 v164, 0xbfb8aa3b, v164
	v_exp_f32_e32 v164, v164
	v_add_f32_e32 v166, 1.0, v166
	v_rcp_f32_e32 v180, v166
	v_mul_f32_e32 v167, 0xbfb8aa3b, v167
	v_add_f32_e32 v164, 1.0, v164
	v_rcp_f32_e32 v164, v164
	v_exp_f32_e32 v167, v167
	v_med3_f32 v146, v146, s66, v179
	v_med3_f32 v157, v157, s66, v179
	v_mul_f32_e32 v164, v166, v164
	v_fmamk_f32 v166, v72, 0x3d000000, v132
	v_mul_f32_e32 v166, 0xbfb8aa3b, v166
	v_exp_f32_e32 v166, v166
	v_add_f32_e32 v167, 1.0, v167
	v_rcp_f32_e32 v181, v167
	v_mov_b32_e32 v168, v147
	v_add_f32_e32 v166, 1.0, v166
	v_rcp_f32_e32 v166, v166
	v_cvt_pk_fp8_f32 v168, v146, v157
	v_med3_f32 v146, v162, s66, v179
	v_med3_f32 v157, v164, s66, v179
	v_mul_f32_e32 v169, v167, v166
	v_fmamk_f32 v166, v73, 0x3d000000, v133
	v_mul_f32_e32 v166, 0xbfb8aa3b, v166
	v_exp_f32_e32 v166, v166
	v_fmamk_f32 v167, v65, 0x3d000000, v129
	v_mul_f32_e32 v167, 0xbfb8aa3b, v167
	v_exp_f32_e32 v167, v167
	v_add_f32_e32 v166, 1.0, v166
	v_rcp_f32_e32 v166, v166
	v_cvt_pk_fp8_f32 v168, v146, v157 op_sel:[0,0,1]
	v_add_f32_e32 v167, 1.0, v167
	v_rcp_f32_e32 v182, v167
	v_mul_f32_e32 v183, v167, v166
	v_fmamk_f32 v166, v74, 0x3d000000, v134
	v_mul_f32_e32 v166, 0xbfb8aa3b, v166
	v_exp_f32_e32 v166, v166
	v_fmamk_f32 v167, v66, 0x3d000000, v130
	v_mul_f32_e32 v167, 0xbfb8aa3b, v167
	v_exp_f32_e32 v167, v167
	v_add_f32_e32 v166, 1.0, v166
	v_rcp_f32_e32 v166, v166
	v_med3_f32 v146, v169, s66, v179
	v_add_f32_e32 v167, 1.0, v167
	v_rcp_f32_e32 v184, v167
	v_mul_f32_e32 v185, v167, v166
	v_fmamk_f32 v166, v75, 0x3d000000, v135
	v_mul_f32_e32 v166, 0xbfb8aa3b, v166
	v_exp_f32_e32 v166, v166
	v_fmamk_f32 v167, v67, 0x3d000000, v131
	v_mul_f32_e32 v167, 0xbfb8aa3b, v167
	v_exp_f32_e32 v167, v167
	v_add_f32_e32 v166, 1.0, v166
	v_rcp_f32_e32 v166, v166
	v_med3_f32 v157, v183, s66, v179
	v_mov_b32_e32 v169, v147
	v_cvt_pk_fp8_f32 v169, v146, v157
	v_add_f32_e32 v167, 1.0, v167
	v_mul_f32_e32 v187, v167, v166
	v_med3_f32 v146, v185, s66, v179
	v_med3_f32 v157, v187, s66, v179
	v_cvt_pk_fp8_f32 v169, v146, v157 op_sel:[0,0,1]
	v_fmamk_f32 v146, v60, 0x3d000000, v140
	v_mul_f32_e32 v146, 0xbfb8aa3b, v146
	v_exp_f32_e32 v146, v146
	v_fmamk_f32 v157, v52, 0x3d000000, v136
	v_mul_f32_e32 v157, 0xbfb8aa3b, v157
	v_exp_f32_e32 v157, v157
	v_add_f32_e32 v146, 1.0, v146
	v_rcp_f32_e32 v146, v146
	v_rcp_f32_e32 v186, v167
	v_add_f32_e32 v157, 1.0, v157
	v_cvt_pk_bf16_f32 v162, v159, v163
	v_rcp_f32_e32 v159, v157
	v_mul_f32_e32 v146, v157, v146
	v_fmamk_f32 v157, v61, 0x3d000000, v141
	s_mov_b64 s[30:31], 0xc000
	v_mul_f32_e32 v157, 0xbfb8aa3b, v157
	v_lshl_add_u64 v[166:167], v[160:161], 0, s[30:31]
	v_exp_f32_e32 v157, v157
	v_cvt_pk_bf16_f32 v163, v165, v180
	v_cvt_pk_bf16_f32 v164, v181, v182
	v_cvt_pk_bf16_f32 v165, v184, v186
	v_lshl_add_u64 v[180:181], s[36:37], 0, v[166:167]
	v_lshl_add_u64 v[166:167], v[166:167], 1, s[38:39]
	global_store_dwordx2 v[180:181], v[168:169], off nt
	global_store_dwordx4 v[166:167], v[162:165], off nt
	v_add_f32_e32 v157, 1.0, v157
	v_rcp_f32_e32 v157, v157
	v_fmamk_f32 v162, v53, 0x3d000000, v137
	v_mul_f32_e32 v162, 0xbfb8aa3b, v162
	v_exp_f32_e32 v162, v162
	v_fmamk_f32 v164, v54, 0x3d000000, v138
	v_mul_f32_e32 v164, 0xbfb8aa3b, v164
	v_exp_f32_e32 v164, v164
	v_add_f32_e32 v162, 1.0, v162
	v_rcp_f32_e32 v163, v162
	v_mul_f32_e32 v157, v162, v157
	v_fmamk_f32 v162, v62, 0x3d000000, v142
	v_mul_f32_e32 v162, 0xbfb8aa3b, v162
	v_exp_f32_e32 v162, v162
	v_add_f32_e32 v164, 1.0, v164
	v_rcp_f32_e32 v165, v164
	v_fmamk_f32 v166, v55, 0x3d000000, v139
; __device__ __forceinline__ unsigned cvt_pk_bf16(float lo, float hi) { f32x2_t v = {lo, hi}; bf16x2_t r = __builtin_convertvector(v, bf16x2_t); return __builtin_bit_cast(unsigned, r); }
; __device__ __forceinline__ float f8c(float v) { return fminf(fmaxf(v, -448.f), 448.f); }
;     __device__ __forceinline__ void operator()(const f32x4 (&acc)[2][2][4][2], const Unit& u, int wr, int wc, int fr, int fq) const {
;     ...
;             const int c0 = 128 * (pn - 26) + lc;
;             f32x4 bA[2], bB[2];
; #pragma unroll
;             for (int n = 0; n < 2; ++n) { bA[n] = *(const f32x4*)(bias + 6656 + c0 + 4 * n); bB[n] = *(const f32x4*)(bias + 7680 + c0 + 4 * n); }
; #pragma unroll
;             for (int ai = 0; ai < 2; ++ai)
; #pragma unroll
;                 for (int m = 0; m < 4; ++m) { const size_t off = (size_t)(row0 + ai * 128 + m * 16) * D + c0; f32x4 rh[2], sb[2];
; #pragma unroll
;                     for (int n = 0; n < 2; ++n) { const f32x4 a = acc[ai][0][m][n] * as + bA[n], b = acc[ai][1][m][n] * as + bB[n];
; #pragma unroll
;                         for (int j = 0; j < 4; ++j) { const float ea = 1.f + __builtin_amdgcn_exp2f(-a[j] * LOG2E), eb = 1.f + __builtin_amdgcn_exp2f(-b[j] * LOG2E); sb[n][j] = __builtin_amdgcn_rcpf(eb); rh[n][j] = eb * __builtin_amdgcn_rcpf(ea); } }
;                     int r0 = 0, r1 = 0; r0 = __builtin_amdgcn_cvt_pk_fp8_f32(f8c(rh[0][0]), f8c(rh[0][1]), r0, false); r0 = __builtin_amdgcn_cvt_pk_fp8_f32(f8c(rh[0][2]), f8c(rh[0][3]), r0, true);
;                     r1 = __builtin_amdgcn_cvt_pk_fp8_f32(f8c(rh[1][0]), f8c(rh[1][1]), r1, false); r1 = __builtin_amdgcn_cvt_pk_fp8_f32(f8c(rh[1][2]), f8c(rh[1][3]), r1, true);
;                     u32x2 w0; w0.x = (unsigned)r0; w0.y = (unsigned)r1; u32x4 w1;
;                     w1.x = cvt_pk_bf16(sb[0][0], sb[0][1]); w1.y = cvt_pk_bf16(sb[0][2], sb[0][3]); w1.z = cvt_pk_bf16(sb[1][0], sb[1][1]); w1.w = cvt_pk_bf16(sb[1][2], sb[1][3]);
;                     *(u32x2*)((unsigned char*)GA + off) = w0; *(u32x4*)(GB + off) = w1; }
	v_add_f32_e32 v162, 1.0, v162
	v_rcp_f32_e32 v162, v162
	v_mul_f32_e32 v166, 0xbfb8aa3b, v166
	v_exp_f32_e32 v166, v166
	v_fmamk_f32 v167, v48, 0x3d000000, v128
	v_mul_f32_e32 v162, v164, v162
	v_fmamk_f32 v164, v63, 0x3d000000, v143
	v_mul_f32_e32 v164, 0xbfb8aa3b, v164
	v_exp_f32_e32 v164, v164
	v_add_f32_e32 v166, 1.0, v166
	v_rcp_f32_e32 v180, v166
	v_mul_f32_e32 v167, 0xbfb8aa3b, v167
	v_add_f32_e32 v164, 1.0, v164
	v_rcp_f32_e32 v164, v164
	v_exp_f32_e32 v167, v167
	v_med3_f32 v146, v146, s66, v179
	v_med3_f32 v157, v157, s66, v179
	v_mul_f32_e32 v164, v166, v164
	v_fmamk_f32 v166, v56, 0x3d000000, v132
	v_mul_f32_e32 v166, 0xbfb8aa3b, v166
	v_exp_f32_e32 v166, v166
	v_add_f32_e32 v167, 1.0, v167
	v_rcp_f32_e32 v181, v167
	v_mov_b32_e32 v168, v147
	v_add_f32_e32 v166, 1.0, v166
	v_rcp_f32_e32 v166, v166
	v_cvt_pk_fp8_f32 v168, v146, v157
	v_med3_f32 v146, v162, s66, v179
	v_med3_f32 v157, v164, s66, v179
	v_mul_f32_e32 v169, v167, v166
	v_fmamk_f32 v166, v57, 0x3d000000, v133
	v_mul_f32_e32 v166, 0xbfb8aa3b, v166
	v_exp_f32_e32 v166, v166
	v_fmamk_f32 v167, v49, 0x3d000000, v129
	v_mul_f32_e32 v167, 0xbfb8aa3b, v167
	v_exp_f32_e32 v167, v167
	v_add_f32_e32 v166, 1.0, v166
	v_rcp_f32_e32 v166, v166
	v_cvt_pk_fp8_f32 v168, v146, v157 op_sel:[0,0,1]
	v_add_f32_e32 v167, 1.0, v167
	v_rcp_f32_e32 v182, v167
	v_mul_f32_e32 v183, v167, v166
	v_fmamk_f32 v166, v58, 0x3d000000, v134
	v_mul_f32_e32 v166, 0xbfb8aa3b, v166
	v_exp_f32_e32 v166, v166
	v_fmamk_f32 v167, v50, 0x3d000000, v130
	v_mul_f32_e32 v167, 0xbfb8aa3b, v167
	v_exp_f32_e32 v167, v167
	v_add_f32_e32 v166, 1.0, v166
	v_rcp_f32_e32 v166, v166
	v_med3_f32 v146, v169, s66, v179
	v_add_f32_e32 v167, 1.0, v167
	v_rcp_f32_e32 v184, v167
	v_mul_f32_e32 v185, v167, v166
	v_fmamk_f32 v166, v59, 0x3d000000, v135
	v_mul_f32_e32 v166, 0xbfb8aa3b, v166
	v_exp_f32_e32 v166, v166
	v_fmamk_f32 v167, v51, 0x3d000000, v131
	v_mul_f32_e32 v167, 0xbfb8aa3b, v167
	v_exp_f32_e32 v167, v167
	v_add_f32_e32 v166, 1.0, v166
	v_rcp_f32_e32 v166, v166
	v_med3_f32 v157, v183, s66, v179
	v_mov_b32_e32 v169, v147
	v_cvt_pk_fp8_f32 v169, v146, v157
	v_add_f32_e32 v167, 1.0, v167
	v_mul_f32_e32 v187, v167, v166
	v_med3_f32 v146, v185, s66, v179
	v_med3_f32 v157, v187, s66, v179
	v_cvt_pk_fp8_f32 v169, v146, v157 op_sel:[0,0,1]
	v_fmamk_f32 v146, v44, 0x3d000000, v140
	v_mul_f32_e32 v146, 0xbfb8aa3b, v146
	v_exp_f32_e32 v146, v146
	v_fmamk_f32 v157, v36, 0x3d000000, v136
	v_mul_f32_e32 v157, 0xbfb8aa3b, v157
	v_exp_f32_e32 v157, v157
	v_add_f32_e32 v146, 1.0, v146
	v_rcp_f32_e32 v146, v146
	v_rcp_f32_e32 v186, v167
	v_add_f32_e32 v157, 1.0, v157
	v_cvt_pk_bf16_f32 v162, v159, v163
	v_rcp_f32_e32 v159, v157
	v_mul_f32_e32 v146, v157, v146
	v_fmamk_f32 v157, v45, 0x3d000000, v141
	s_mov_b64 s[30:31], 0x20000
	v_mul_f32_e32 v157, 0xbfb8aa3b, v157
	v_lshl_add_u64 v[166:167], v[160:161], 0, s[30:31]
	v_exp_f32_e32 v157, v157
	v_cvt_pk_bf16_f32 v163, v165, v180
	v_cvt_pk_bf16_f32 v164, v181, v182
	v_cvt_pk_bf16_f32 v165, v184, v186
	v_lshl_add_u64 v[180:181], s[36:37], 0, v[166:167]
	v_lshl_add_u64 v[166:167], v[166:167], 1, s[38:39]
	global_store_dwordx2 v[180:181], v[168:169], off nt
	global_store_dwordx4 v[166:167], v[162:165], off nt
	v_add_f32_e32 v157, 1.0, v157
	v_rcp_f32_e32 v157, v157
	v_fmamk_f32 v162, v37, 0x3d000000, v137
	v_mul_f32_e32 v162, 0xbfb8aa3b, v162
	v_exp_f32_e32 v162, v162
	v_fmamk_f32 v164, v38, 0x3d000000, v138
	v_mul_f32_e32 v164, 0xbfb8aa3b, v164
	v_exp_f32_e32 v164, v164
	v_add_f32_e32 v162, 1.0, v162
	v_rcp_f32_e32 v163, v162
	v_mul_f32_e32 v157, v162, v157
	v_fmamk_f32 v162, v46, 0x3d000000, v142
	v_mul_f32_e32 v162, 0xbfb8aa3b, v162
	v_exp_f32_e32 v162, v162
	v_add_f32_e32 v164, 1.0, v164
	v_rcp_f32_e32 v165, v164
	v_fmamk_f32 v166, v39, 0x3d000000, v139
	v_add_f32_e32 v162, 1.0, v162
	v_rcp_f32_e32 v162, v162
	v_mul_f32_e32 v166, 0xbfb8aa3b, v166
	v_exp_f32_e32 v166, v166
	v_fmamk_f32 v167, v32, 0x3d000000, v128
	v_mul_f32_e32 v162, v164, v162
	v_fmamk_f32 v164, v47, 0x3d000000, v143
	v_mul_f32_e32 v164, 0xbfb8aa3b, v164
	v_exp_f32_e32 v164, v164
	v_add_f32_e32 v166, 1.0, v166
	v_rcp_f32_e32 v180, v166
	v_mul_f32_e32 v167, 0xbfb8aa3b, v167
	v_add_f32_e32 v164, 1.0, v164
	v_rcp_f32_e32 v164, v164
	v_exp_f32_e32 v167, v167
	v_med3_f32 v146, v146, s66, v179
	v_med3_f32 v157, v157, s66, v179
	v_mul_f32_e32 v164, v166, v164
	v_fmamk_f32 v166, v40, 0x3d000000, v132
	v_mul_f32_e32 v166, 0xbfb8aa3b, v166
	v_exp_f32_e32 v166, v166
	v_add_f32_e32 v167, 1.0, v167
	v_rcp_f32_e32 v181, v167
	v_mov_b32_e32 v168, v147
	v_add_f32_e32 v166, 1.0, v166
	v_rcp_f32_e32 v166, v166
	v_cvt_pk_fp8_f32 v168, v146, v157
	v_med3_f32 v146, v162, s66, v179
	v_med3_f32 v157, v164, s66, v179
	v_mul_f32_e32 v169, v167, v166
	v_fmamk_f32 v166, v41, 0x3d000000, v133
	v_mul_f32_e32 v166, 0xbfb8aa3b, v166
	v_exp_f32_e32 v166, v166
	v_fmamk_f32 v167, v33, 0x3d000000, v129
	v_mul_f32_e32 v167, 0xbfb8aa3b, v167
	v_exp_f32_e32 v167, v167
	v_add_f32_e32 v166, 1.0, v166
	v_rcp_f32_e32 v166, v166
	v_cvt_pk_fp8_f32 v168, v146, v157 op_sel:[0,0,1]
	v_add_f32_e32 v167, 1.0, v167
	v_rcp_f32_e32 v182, v167
	v_mul_f32_e32 v183, v167, v166
	v_fmamk_f32 v166, v42, 0x3d000000, v134
	v_mul_f32_e32 v166, 0xbfb8aa3b, v166
	v_exp_f32_e32 v166, v166
	v_fmamk_f32 v167, v34, 0x3d000000, v130
	v_mul_f32_e32 v167, 0xbfb8aa3b, v167
	v_exp_f32_e32 v167, v167
	v_add_f32_e32 v166, 1.0, v166
	v_rcp_f32_e32 v166, v166
	v_med3_f32 v146, v169, s66, v179
	v_add_f32_e32 v167, 1.0, v167
	v_rcp_f32_e32 v184, v167
	v_mul_f32_e32 v185, v167, v166
	v_fmamk_f32 v166, v43, 0x3d000000, v135
	v_mul_f32_e32 v166, 0xbfb8aa3b, v166
	v_exp_f32_e32 v166, v166
; __device__ __forceinline__ unsigned cvt_pk_bf16(float lo, float hi) { f32x2_t v = {lo, hi}; bf16x2_t r = __builtin_convertvector(v, bf16x2_t); return __builtin_bit_cast(unsigned, r); }
; __device__ __forceinline__ float f8c(float v) { return fminf(fmaxf(v, -448.f), 448.f); }
;     __device__ __forceinline__ void operator()(const f32x4 (&acc)[2][2][4][2], const Unit& u, int wr, int wc, int fr, int fq) const {
;     ...
;             const int c0 = 128 * (pn - 26) + lc;
;             f32x4 bA[2], bB[2];
; #pragma unroll
;             for (int n = 0; n < 2; ++n) { bA[n] = *(const f32x4*)(bias + 6656 + c0 + 4 * n); bB[n] = *(const f32x4*)(bias + 7680 + c0 + 4 * n); }
; #pragma unroll
;             for (int ai = 0; ai < 2; ++ai)
; #pragma unroll
;                 for (int m = 0; m < 4; ++m) { const size_t off = (size_t)(row0 + ai * 128 + m * 16) * D + c0; f32x4 rh[2], sb[2];
; #pragma unroll
;                     for (int n = 0; n < 2; ++n) { const f32x4 a = acc[ai][0][m][n] * as + bA[n], b = acc[ai][1][m][n] * as + bB[n];
; #pragma unroll
;                         for (int j = 0; j < 4; ++j) { const float ea = 1.f + __builtin_amdgcn_exp2f(-a[j] * LOG2E), eb = 1.f + __builtin_amdgcn_exp2f(-b[j] * LOG2E); sb[n][j] = __builtin_amdgcn_rcpf(eb); rh[n][j] = eb * __builtin_amdgcn_rcpf(ea); } }
;                     int r0 = 0, r1 = 0; r0 = __builtin_amdgcn_cvt_pk_fp8_f32(f8c(rh[0][0]), f8c(rh[0][1]), r0, false); r0 = __builtin_amdgcn_cvt_pk_fp8_f32(f8c(rh[0][2]), f8c(rh[0][3]), r0, true);
;                     r1 = __builtin_amdgcn_cvt_pk_fp8_f32(f8c(rh[1][0]), f8c(rh[1][1]), r1, false); r1 = __builtin_amdgcn_cvt_pk_fp8_f32(f8c(rh[1][2]), f8c(rh[1][3]), r1, true);
;                     u32x2 w0; w0.x = (unsigned)r0; w0.y = (unsigned)r1; u32x4 w1;
;                     w1.x = cvt_pk_bf16(sb[0][0], sb[0][1]); w1.y = cvt_pk_bf16(sb[0][2], sb[0][3]); w1.z = cvt_pk_bf16(sb[1][0], sb[1][1]); w1.w = cvt_pk_bf16(sb[1][2], sb[1][3]);
;                     *(u32x2*)((unsigned char*)GA + off) = w0; *(u32x4*)(GB + off) = w1; }
	v_fmamk_f32 v167, v35, 0x3d000000, v131
	v_mul_f32_e32 v167, 0xbfb8aa3b, v167
	v_exp_f32_e32 v167, v167
	v_add_f32_e32 v166, 1.0, v166
	v_rcp_f32_e32 v166, v166
	v_med3_f32 v157, v183, s66, v179
	v_mov_b32_e32 v169, v147
	v_cvt_pk_fp8_f32 v169, v146, v157
	v_add_f32_e32 v167, 1.0, v167
	v_mul_f32_e32 v187, v167, v166
	v_med3_f32 v146, v185, s66, v179
	v_med3_f32 v157, v187, s66, v179
	v_cvt_pk_fp8_f32 v169, v146, v157 op_sel:[0,0,1]
	v_fmamk_f32 v146, v28, 0x3d000000, v140
	v_mul_f32_e32 v146, 0xbfb8aa3b, v146
	v_exp_f32_e32 v146, v146
	v_fmamk_f32 v157, v20, 0x3d000000, v136
	v_mul_f32_e32 v157, 0xbfb8aa3b, v157
	v_exp_f32_e32 v157, v157
	v_add_f32_e32 v146, 1.0, v146
	v_rcp_f32_e32 v146, v146
	v_rcp_f32_e32 v186, v167
	v_add_f32_e32 v157, 1.0, v157
	v_cvt_pk_bf16_f32 v162, v159, v163
	v_rcp_f32_e32 v159, v157
	v_mul_f32_e32 v146, v157, v146
	v_fmamk_f32 v157, v29, 0x3d000000, v141
	s_mov_b64 s[30:31], 0x24000
	v_mul_f32_e32 v157, 0xbfb8aa3b, v157
	v_lshl_add_u64 v[166:167], v[160:161], 0, s[30:31]
	v_exp_f32_e32 v157, v157
	v_cvt_pk_bf16_f32 v163, v165, v180
	v_cvt_pk_bf16_f32 v164, v181, v182
	v_cvt_pk_bf16_f32 v165, v184, v186
	v_lshl_add_u64 v[180:181], s[36:37], 0, v[166:167]
	v_lshl_add_u64 v[166:167], v[166:167], 1, s[38:39]
	global_store_dwordx2 v[180:181], v[168:169], off nt
	global_store_dwordx4 v[166:167], v[162:165], off nt
	v_add_f32_e32 v157, 1.0, v157
	v_rcp_f32_e32 v157, v157
	v_fmamk_f32 v162, v21, 0x3d000000, v137
	v_mul_f32_e32 v162, 0xbfb8aa3b, v162
	v_exp_f32_e32 v162, v162
	v_fmamk_f32 v164, v22, 0x3d000000, v138
	v_mul_f32_e32 v164, 0xbfb8aa3b, v164
	v_exp_f32_e32 v164, v164
	v_add_f32_e32 v162, 1.0, v162
	v_rcp_f32_e32 v163, v162
	v_mul_f32_e32 v157, v162, v157
	v_fmamk_f32 v162, v30, 0x3d000000, v142
	v_mul_f32_e32 v162, 0xbfb8aa3b, v162
	v_exp_f32_e32 v162, v162
	v_add_f32_e32 v164, 1.0, v164
	v_rcp_f32_e32 v165, v164
	v_fmamk_f32 v166, v23, 0x3d000000, v139
	v_add_f32_e32 v162, 1.0, v162
	v_rcp_f32_e32 v162, v162
	v_mul_f32_e32 v166, 0xbfb8aa3b, v166
	v_exp_f32_e32 v166, v166
	v_fmamk_f32 v167, v16, 0x3d000000, v128
	v_mul_f32_e32 v162, v164, v162
	v_fmamk_f32 v164, v31, 0x3d000000, v143
	v_mul_f32_e32 v164, 0xbfb8aa3b, v164
	v_exp_f32_e32 v164, v164
	v_add_f32_e32 v166, 1.0, v166
	v_rcp_f32_e32 v180, v166
	v_mul_f32_e32 v167, 0xbfb8aa3b, v167
	v_add_f32_e32 v164, 1.0, v164
	v_rcp_f32_e32 v164, v164
	v_exp_f32_e32 v167, v167
	v_fmamk_f32 v140, v12, 0x3d000000, v140
	v_med3_f32 v146, v146, s66, v179
	v_mul_f32_e32 v164, v166, v164
	v_fmamk_f32 v166, v24, 0x3d000000, v132
	v_mul_f32_e32 v166, 0xbfb8aa3b, v166
	v_exp_f32_e32 v166, v166
	v_add_f32_e32 v167, 1.0, v167
	v_rcp_f32_e32 v181, v167
	v_med3_f32 v157, v157, s66, v179
	v_add_f32_e32 v166, 1.0, v166
	v_rcp_f32_e32 v166, v166
	v_mov_b32_e32 v168, v147
	v_mul_f32_e32 v140, 0xbfb8aa3b, v140
	v_cvt_pk_fp8_f32 v168, v146, v157
	v_mul_f32_e32 v169, v167, v166
	v_fmamk_f32 v166, v25, 0x3d000000, v133
	v_mul_f32_e32 v166, 0xbfb8aa3b, v166
	v_exp_f32_e32 v166, v166
	v_fmamk_f32 v167, v17, 0x3d000000, v129
	v_mul_f32_e32 v167, 0xbfb8aa3b, v167
	v_exp_f32_e32 v167, v167
	v_add_f32_e32 v166, 1.0, v166
	v_rcp_f32_e32 v166, v166
	v_exp_f32_e32 v140, v140
	v_add_f32_e32 v167, 1.0, v167
	v_rcp_f32_e32 v182, v167
	v_mul_f32_e32 v183, v167, v166
	v_fmamk_f32 v166, v26, 0x3d000000, v134
	v_mul_f32_e32 v166, 0xbfb8aa3b, v166
	v_exp_f32_e32 v166, v166
	v_fmamk_f32 v167, v18, 0x3d000000, v130
	v_mul_f32_e32 v167, 0xbfb8aa3b, v167
	v_exp_f32_e32 v167, v167
	v_add_f32_e32 v166, 1.0, v166
	v_rcp_f32_e32 v166, v166
	v_fmamk_f32 v136, v4, 0x3d000000, v136
	v_add_f32_e32 v167, 1.0, v167
	v_rcp_f32_e32 v184, v167
	v_mul_f32_e32 v185, v167, v166
	v_fmamk_f32 v166, v27, 0x3d000000, v135
	v_mul_f32_e32 v166, 0xbfb8aa3b, v166
	v_exp_f32_e32 v166, v166
	v_fmamk_f32 v167, v19, 0x3d000000, v131
	v_mul_f32_e32 v167, 0xbfb8aa3b, v167
	v_exp_f32_e32 v167, v167
	v_add_f32_e32 v166, 1.0, v166
	v_rcp_f32_e32 v166, v166
	v_med3_f32 v146, v162, s66, v179
	v_med3_f32 v157, v164, s66, v179
	v_mul_f32_e32 v136, 0xbfb8aa3b, v136
	v_cvt_pk_fp8_f32 v168, v146, v157 op_sel:[0,0,1]
	v_med3_f32 v146, v169, s66, v179
	v_med3_f32 v157, v183, s66, v179
	v_mov_b32_e32 v169, v147
	v_add_f32_e32 v140, 1.0, v140
	v_exp_f32_e32 v136, v136
; __device__ __forceinline__ unsigned cvt_pk_bf16(float lo, float hi) { f32x2_t v = {lo, hi}; bf16x2_t r = __builtin_convertvector(v, bf16x2_t); return __builtin_bit_cast(unsigned, r); }
; __device__ __forceinline__ float f8c(float v) { return fminf(fmaxf(v, -448.f), 448.f); }
;     __device__ __forceinline__ void operator()(const f32x4 (&acc)[2][2][4][2], const Unit& u, int wr, int wc, int fr, int fq) const {
;     ...
;             const int c0 = 128 * (pn - 26) + lc;
;             f32x4 bA[2], bB[2];
; #pragma unroll
;             for (int n = 0; n < 2; ++n) { bA[n] = *(const f32x4*)(bias + 6656 + c0 + 4 * n); bB[n] = *(const f32x4*)(bias + 7680 + c0 + 4 * n); }
; #pragma unroll
;             for (int ai = 0; ai < 2; ++ai)
; #pragma unroll
;                 for (int m = 0; m < 4; ++m) { const size_t off = (size_t)(row0 + ai * 128 + m * 16) * D + c0; f32x4 rh[2], sb[2];
; #pragma unroll
;                     for (int n = 0; n < 2; ++n) { const f32x4 a = acc[ai][0][m][n] * as + bA[n], b = acc[ai][1][m][n] * as + bB[n];
; #pragma unroll
;                         for (int j = 0; j < 4; ++j) { const float ea = 1.f + __builtin_amdgcn_exp2f(-a[j] * LOG2E), eb = 1.f + __builtin_amdgcn_exp2f(-b[j] * LOG2E); sb[n][j] = __builtin_amdgcn_rcpf(eb); rh[n][j] = eb * __builtin_amdgcn_rcpf(ea); } }
;                     int r0 = 0, r1 = 0; r0 = __builtin_amdgcn_cvt_pk_fp8_f32(f8c(rh[0][0]), f8c(rh[0][1]), r0, false); r0 = __builtin_amdgcn_cvt_pk_fp8_f32(f8c(rh[0][2]), f8c(rh[0][3]), r0, true);
;                     r1 = __builtin_amdgcn_cvt_pk_fp8_f32(f8c(rh[1][0]), f8c(rh[1][1]), r1, false); r1 = __builtin_amdgcn_cvt_pk_fp8_f32(f8c(rh[1][2]), f8c(rh[1][3]), r1, true);
;                     u32x2 w0; w0.x = (unsigned)r0; w0.y = (unsigned)r1; u32x4 w1;
;                     w1.x = cvt_pk_bf16(sb[0][0], sb[0][1]); w1.y = cvt_pk_bf16(sb[0][2], sb[0][3]); w1.z = cvt_pk_bf16(sb[1][0], sb[1][1]); w1.w = cvt_pk_bf16(sb[1][2], sb[1][3]);
;                     *(u32x2*)((unsigned char*)GA + off) = w0; *(u32x4*)(GB + off) = w1; }
	v_cvt_pk_fp8_f32 v169, v146, v157
	v_rcp_f32_e32 v140, v140
	v_add_f32_e32 v167, 1.0, v167
	v_mul_f32_e32 v187, v167, v166
	v_med3_f32 v146, v185, s66, v179
	v_med3_f32 v157, v187, s66, v179
	v_add_f32_e32 v136, 1.0, v136
	v_cvt_pk_fp8_f32 v169, v146, v157 op_sel:[0,0,1]
	v_rcp_f32_e32 v146, v136
	v_mul_f32_e32 v136, v136, v140
	v_fmamk_f32 v140, v13, 0x3d000000, v141
	v_mul_f32_e32 v140, 0xbfb8aa3b, v140
	v_exp_f32_e32 v140, v140
	v_fmamk_f32 v137, v5, 0x3d000000, v137
	v_mul_f32_e32 v137, 0xbfb8aa3b, v137
	v_exp_f32_e32 v137, v137
	v_add_f32_e32 v140, 1.0, v140
	v_rcp_f32_e32 v140, v140
	v_fmamk_f32 v138, v6, 0x3d000000, v138
	v_add_f32_e32 v137, 1.0, v137
	v_rcp_f32_e32 v141, v137
	v_mul_f32_e32 v137, v137, v140
	v_fmamk_f32 v140, v14, 0x3d000000, v142
	v_mul_f32_e32 v140, 0xbfb8aa3b, v140
	v_exp_f32_e32 v140, v140
	v_mul_f32_e32 v138, 0xbfb8aa3b, v138
	v_exp_f32_e32 v138, v138
	v_fmac_f32_e32 v143, 0x3d000000, v15
	v_add_f32_e32 v140, 1.0, v140
	v_rcp_f32_e32 v140, v140
	v_add_f32_e32 v138, 1.0, v138
	v_fmamk_f32 v132, v8, 0x3d000000, v132
	v_rcp_f32_e32 v142, v138
	v_mul_f32_e32 v138, v138, v140
	v_mul_f32_e32 v140, 0xbfb8aa3b, v143
	v_mul_f32_e32 v132, 0xbfb8aa3b, v132
	v_exp_f32_e32 v140, v140
	v_exp_f32_e32 v132, v132
	v_fmac_f32_e32 v139, 0x3d000000, v7
	v_fmamk_f32 v128, v0, 0x3d000000, v128
	v_mul_f32_e32 v139, 0xbfb8aa3b, v139
	v_mul_f32_e32 v128, 0xbfb8aa3b, v128
	v_add_f32_e32 v140, 1.0, v140
	v_exp_f32_e32 v139, v139
	v_add_f32_e32 v132, 1.0, v132
	v_exp_f32_e32 v128, v128
	v_rcp_f32_e32 v140, v140
	v_rcp_f32_e32 v132, v132
	v_add_f32_e32 v139, 1.0, v139
	v_add_f32_e32 v128, 1.0, v128
	v_rcp_f32_e32 v143, v139
	v_mul_f32_e32 v139, v139, v140
	v_rcp_f32_e32 v140, v128
	v_mul_f32_e32 v128, v128, v132
	v_fmamk_f32 v132, v9, 0x3d000000, v133
	v_mul_f32_e32 v132, 0xbfb8aa3b, v132
	v_exp_f32_e32 v132, v132
	v_fmamk_f32 v129, v1, 0x3d000000, v129
	v_mul_f32_e32 v129, 0xbfb8aa3b, v129
	v_exp_f32_e32 v129, v129
	v_add_f32_e32 v132, 1.0, v132
	v_rcp_f32_e32 v132, v132
	v_fmamk_f32 v130, v2, 0x3d000000, v130
	v_add_f32_e32 v129, 1.0, v129
	v_rcp_f32_e32 v157, v129
	v_mul_f32_e32 v129, v129, v132
	v_fmamk_f32 v132, v10, 0x3d000000, v134
	v_mul_f32_e32 v132, 0xbfb8aa3b, v132
	v_exp_f32_e32 v132, v132
	v_mul_f32_e32 v130, 0xbfb8aa3b, v130
	v_exp_f32_e32 v130, v130
	v_fmac_f32_e32 v135, 0x3d000000, v11
	v_add_f32_e32 v132, 1.0, v132
	v_rcp_f32_e32 v132, v132
	v_add_f32_e32 v130, 1.0, v130
	v_cvt_pk_bf16_f32 v162, v159, v163
	v_rcp_f32_e32 v159, v130
	v_mul_f32_e32 v130, v130, v132
	v_mul_f32_e32 v132, 0xbfb8aa3b, v135
	v_exp_f32_e32 v132, v132
	v_med3_f32 v135, v136, s66, v179
	v_med3_f32 v136, v137, s66, v179
	v_mov_b32_e32 v134, v147
	v_fmac_f32_e32 v131, 0x3d000000, v3
	v_cvt_pk_fp8_f32 v134, v135, v136
	v_mul_f32_e32 v131, 0xbfb8aa3b, v131
	v_rcp_f32_e32 v186, v167
	v_add_f32_e32 v132, 1.0, v132
	v_exp_f32_e32 v131, v131
	v_rcp_f32_e32 v132, v132
	v_med3_f32 v135, v138, s66, v179
	v_med3_f32 v136, v139, s66, v179
	s_mov_b64 s[30:31], 0x28000
	v_cvt_pk_fp8_f32 v134, v135, v136 op_sel:[0,0,1]
	v_med3_f32 v128, v128, s66, v179
	v_med3_f32 v129, v129, s66, v179
	v_mov_b32_e32 v135, v147
	v_lshl_add_u64 v[166:167], v[160:161], 0, s[30:31]
	v_cvt_pk_fp8_f32 v135, v128, v129
	v_cvt_pk_bf16_f32 v163, v165, v180
	v_cvt_pk_bf16_f32 v164, v181, v182
	v_cvt_pk_bf16_f32 v165, v184, v186
	v_lshl_add_u64 v[180:181], s[36:37], 0, v[166:167]
	v_lshl_add_u64 v[166:167], v[166:167], 1, s[38:39]
	v_add_f32_e32 v131, 1.0, v131
	global_store_dwordx2 v[180:181], v[168:169], off nt
	global_store_dwordx4 v[166:167], v[162:165], off nt
	v_med3_f32 v128, v130, s66, v179
	s_mov_b64 s[30:31], 0x2c000
	v_rcp_f32_e32 v162, v131
	v_mul_f32_e32 v131, v131, v132
	v_med3_f32 v129, v131, s66, v179
	v_cvt_pk_fp8_f32 v135, v128, v129 op_sel:[0,0,1]
	v_lshl_add_u64 v[132:133], v[160:161], 0, s[30:31]
	v_cvt_pk_bf16_f32 v128, v146, v141
	v_cvt_pk_bf16_f32 v129, v142, v143
	v_cvt_pk_bf16_f32 v130, v140, v157
	v_cvt_pk_bf16_f32 v131, v159, v162
	v_lshl_add_u64 v[136:137], s[36:37], 0, v[132:133]
	v_lshl_add_u64 v[132:133], v[132:133], 1, s[38:39]
	global_store_dwordx2 v[136:137], v[134:135], off nt
	global_store_dwordx4 v[132:133], v[128:131], off nt
	s_mov_b64 s[30:31], 0
